# grid barrier: non-leader workgroups poll the top-level generation word directly instead of waiting for their XCD leader to re-publish it
# speedup vs baseline: 1.0086x; 1.0086x over previous
; __device__ __forceinline__ unsigned xb_ld(unsigned* p)              { return __hip_atomic_load(p, __ATOMIC_RELAXED, __HIP_MEMORY_SCOPE_AGENT); }
; __device__ __forceinline__ unsigned xb_add(unsigned* p, unsigned v) { return __hip_atomic_fetch_add(p, v, __ATOMIC_RELAXED, __HIP_MEMORY_SCOPE_AGENT); }
; #define XB_SPIN(cond, bar) do { unsigned _sp = 0; while (cond) { __builtin_amdgcn_s_sleep(0); \
;     if ((++_sp & 255u) == 0u) { if (xb_ld(&(bar)[XB_TMO])) break; if (_sp > XB_SPIN_CAP) { atomicAdd(&(bar)[XB_TMO], 1u); break; } } } } while (0)
; __device__ __forceinline__ void xcd_barrier(const XcdBarrier& b) {
;     ...
;         const unsigned old = xb_add(&bar[XB_XSUB(b.x)], 1u);
;         const unsigned gen = old / nloc;
;         if (old + 1u == (gen + 1u) * nloc) {
;     ...
;             XB_SPIN(xb_ld(&bar[XB_XGEN(b.x)]) == gen, bar);
.LBB0_155:
	s_or_b64 exec, exec, s[0:1]
	v_cvt_f32_u32_e32 v4, v2
	s_waitcnt vmcnt(0)
	v_readfirstlane_b32 s0, v3
	v_sub_u32_e32 v3, 0, v2
	v_rcp_iflag_f32_e32 v4, v4
	v_add_u32_e32 v5, s0, v1
	v_mul_f32_e32 v4, 0x4f7ffffe, v4
	v_cvt_u32_f32_e32 v4, v4
	v_mul_lo_u32 v1, v3, v4
	v_mul_hi_u32 v1, v4, v1
	v_add_u32_e32 v1, v4, v1
	v_mul_hi_u32 v1, v5, v1
	v_mul_lo_u32 v3, v1, v2
	v_sub_u32_e32 v3, v5, v3
	v_add_u32_e32 v4, 1, v1
	v_cmp_ge_u32_e32 vcc, v3, v2
	s_nop 1
	v_cndmask_b32_e32 v1, v1, v4, vcc
	v_sub_u32_e32 v4, v3, v2
	v_cndmask_b32_e32 v3, v3, v4, vcc
	v_add_u32_e32 v4, 1, v1
	v_cmp_ge_u32_e32 vcc, v3, v2
	v_add_u32_e32 v3, 1, v5
	s_nop 0
	v_cndmask_b32_e32 v1, v1, v4, vcc
	v_mul_lo_u32 v4, v2, v1
	v_add_u32_e32 v2, v4, v2
	v_cmp_ne_u32_e32 vcc, v3, v2
	s_and_saveexec_b64 s[0:1], vcc
	s_xor_b64 s[0:1], exec, s[0:1]
	s_cbranch_execz .LBB0_169
	v_readlane_b32 s2, v252, 9
	v_readlane_b32 s3, v252, 10
	s_waitcnt lgkmcnt(0)
	s_nop 3
	global_load_dword v0, v17, s[2:3] sc1
	s_waitcnt vmcnt(0)
	v_cmp_eq_u32_e32 vcc, v0, v1
	s_and_saveexec_b64 s[2:3], vcc
	s_cbranch_execz .LBB0_168
	s_mov_b32 s17, 1
	s_mov_b64 s[6:7], 0
	s_branch .LBB0_159

; __device__ __forceinline__ unsigned xb_ld(unsigned* p)              { return __hip_atomic_load(p, __ATOMIC_RELAXED, __HIP_MEMORY_SCOPE_AGENT); }
; #define XB_SPIN(cond, bar) do { unsigned _sp = 0; while (cond) { __builtin_amdgcn_s_sleep(0); \
;     if ((++_sp & 255u) == 0u) { if (xb_ld(&(bar)[XB_TMO])) break; if (_sp > XB_SPIN_CAP) { atomicAdd(&(bar)[XB_TMO], 1u); break; } } } } while (0)
; __device__ __forceinline__ void xcd_barrier(const XcdBarrier& b) {
;     ...
;             XB_SPIN(xb_ld(&bar[XB_XGEN(b.x)]) == gen, bar);
.LBB0_163:
	v_readlane_b32 s10, v252, 9
	v_readlane_b32 s11, v252, 10
	s_add_i32 s17, s17, 1
	s_mov_b64 s[12:13], -1
	s_nop 2
	global_load_dword v0, v17, s[10:11] sc1
	s_waitcnt vmcnt(0)
	v_cmp_ne_u32_e32 vcc, v0, v1
	s_orn2_b64 s[10:11], vcc, exec
	s_branch .LBB0_158

; __device__ __forceinline__ unsigned xb_ld(unsigned* p)              { return __hip_atomic_load(p, __ATOMIC_RELAXED, __HIP_MEMORY_SCOPE_AGENT); }
; __device__ __forceinline__ unsigned xb_add(unsigned* p, unsigned v) { return __hip_atomic_fetch_add(p, v, __ATOMIC_RELAXED, __HIP_MEMORY_SCOPE_AGENT); }
; #define XB_SPIN(cond, bar) do { unsigned _sp = 0; while (cond) { __builtin_amdgcn_s_sleep(0); \
;     if ((++_sp & 255u) == 0u) { if (xb_ld(&(bar)[XB_TMO])) break; if (_sp > XB_SPIN_CAP) { atomicAdd(&(bar)[XB_TMO], 1u); break; } } } } while (0)
; __device__ __forceinline__ void xcd_barrier(const XcdBarrier& b) {
;     ...
;         const unsigned old = xb_add(&bar[XB_XSUB(b.x)], 1u);
;         const unsigned gen = old / nloc;
;         if (old + 1u == (gen + 1u) * nloc) {
;     ...
;             XB_SPIN(xb_ld(&bar[XB_XGEN(b.x)]) == gen, bar);
.LBB0_244:
	s_or_b64 exec, exec, s[0:1]
	v_cvt_f32_u32_e32 v4, v2
	s_waitcnt vmcnt(0)
	v_readfirstlane_b32 s0, v3
	v_sub_u32_e32 v3, 0, v2
	v_rcp_iflag_f32_e32 v4, v4
	v_add_u32_e32 v5, s0, v1
	v_mul_f32_e32 v4, 0x4f7ffffe, v4
	v_cvt_u32_f32_e32 v4, v4
	v_mul_lo_u32 v1, v3, v4
	v_mul_hi_u32 v1, v4, v1
	v_add_u32_e32 v1, v4, v1
	v_mul_hi_u32 v1, v5, v1
	v_mul_lo_u32 v3, v1, v2
	v_sub_u32_e32 v3, v5, v3
	v_add_u32_e32 v4, 1, v1
	v_cmp_ge_u32_e32 vcc, v3, v2
	s_nop 1
	v_cndmask_b32_e32 v1, v1, v4, vcc
	v_sub_u32_e32 v4, v3, v2
	v_cndmask_b32_e32 v3, v3, v4, vcc
	v_add_u32_e32 v4, 1, v1
	v_cmp_ge_u32_e32 vcc, v3, v2
	v_add_u32_e32 v3, 1, v5
	s_nop 0
	v_cndmask_b32_e32 v1, v1, v4, vcc
	v_mul_lo_u32 v4, v2, v1
	v_add_u32_e32 v2, v4, v2
	v_cmp_ne_u32_e32 vcc, v3, v2
	s_and_saveexec_b64 s[0:1], vcc
	s_xor_b64 s[0:1], exec, s[0:1]
	s_cbranch_execz .LBB0_258
	v_readlane_b32 s2, v252, 9
	v_readlane_b32 s3, v252, 10
	s_waitcnt lgkmcnt(0)
	s_nop 3
	global_load_dword v0, v17, s[2:3] sc1
	s_waitcnt vmcnt(0)
	v_cmp_eq_u32_e32 vcc, v0, v1
	s_and_saveexec_b64 s[2:3], vcc
	s_cbranch_execz .LBB0_257
	s_mov_b32 s19, 1
	s_mov_b64 s[8:9], 0
	s_branch .LBB0_248

; __device__ __forceinline__ unsigned xb_ld(unsigned* p)              { return __hip_atomic_load(p, __ATOMIC_RELAXED, __HIP_MEMORY_SCOPE_AGENT); }
; #define XB_SPIN(cond, bar) do { unsigned _sp = 0; while (cond) { __builtin_amdgcn_s_sleep(0); \
;     if ((++_sp & 255u) == 0u) { if (xb_ld(&(bar)[XB_TMO])) break; if (_sp > XB_SPIN_CAP) { atomicAdd(&(bar)[XB_TMO], 1u); break; } } } } while (0)
; __device__ __forceinline__ void xcd_barrier(const XcdBarrier& b) {
;     ...
;             XB_SPIN(xb_ld(&bar[XB_XGEN(b.x)]) == gen, bar);
.LBB0_252:
	v_readlane_b32 s12, v252, 9
	v_readlane_b32 s13, v252, 10
	s_add_i32 s19, s19, 1
	s_mov_b64 s[14:15], -1
	s_nop 2
	global_load_dword v0, v17, s[12:13] sc1
	s_waitcnt vmcnt(0)
	v_cmp_ne_u32_e32 vcc, v0, v1
	s_orn2_b64 s[12:13], vcc, exec
	s_branch .LBB0_247

; __device__ __forceinline__ unsigned xb_ld(unsigned* p)              { return __hip_atomic_load(p, __ATOMIC_RELAXED, __HIP_MEMORY_SCOPE_AGENT); }
; __device__ __forceinline__ unsigned xb_add(unsigned* p, unsigned v) { return __hip_atomic_fetch_add(p, v, __ATOMIC_RELAXED, __HIP_MEMORY_SCOPE_AGENT); }
; #define XB_SPIN(cond, bar) do { unsigned _sp = 0; while (cond) { __builtin_amdgcn_s_sleep(0); \
;     if ((++_sp & 255u) == 0u) { if (xb_ld(&(bar)[XB_TMO])) break; if (_sp > XB_SPIN_CAP) { atomicAdd(&(bar)[XB_TMO], 1u); break; } } } } while (0)
; __device__ __forceinline__ void xcd_barrier(const XcdBarrier& b) {
;     ...
;         const unsigned old = xb_add(&bar[XB_XSUB(b.x)], 1u);
;         const unsigned gen = old / nloc;
;         if (old + 1u == (gen + 1u) * nloc) {
;     ...
;             XB_SPIN(xb_ld(&bar[XB_XGEN(b.x)]) == gen, bar);
.LBB0_1997:
	s_or_b64 exec, exec, s[0:1]
	v_cvt_f32_u32_e32 v4, v2
	s_waitcnt vmcnt(0)
	v_readfirstlane_b32 s0, v3
	v_sub_u32_e32 v3, 0, v2
	v_rcp_iflag_f32_e32 v4, v4
	v_add_u32_e32 v5, s0, v1
	v_mul_f32_e32 v4, 0x4f7ffffe, v4
	v_cvt_u32_f32_e32 v4, v4
	v_mul_lo_u32 v1, v3, v4
	v_mul_hi_u32 v1, v4, v1
	v_add_u32_e32 v1, v4, v1
	v_mul_hi_u32 v1, v5, v1
	v_mul_lo_u32 v3, v1, v2
	v_sub_u32_e32 v3, v5, v3
	v_add_u32_e32 v4, 1, v1
	v_cmp_ge_u32_e32 vcc, v3, v2
	s_nop 1
	v_cndmask_b32_e32 v1, v1, v4, vcc
	v_sub_u32_e32 v4, v3, v2
	v_cndmask_b32_e32 v3, v3, v4, vcc
	v_add_u32_e32 v4, 1, v1
	v_cmp_ge_u32_e32 vcc, v3, v2
	v_add_u32_e32 v3, 1, v5
	s_nop 0
	v_cndmask_b32_e32 v1, v1, v4, vcc
	v_mul_lo_u32 v4, v2, v1
	v_add_u32_e32 v2, v4, v2
	v_cmp_ne_u32_e32 vcc, v3, v2
	s_and_saveexec_b64 s[0:1], vcc
	s_xor_b64 s[0:1], exec, s[0:1]
	s_cbranch_execz .LBB0_2011
	v_readlane_b32 s2, v252, 9
	v_readlane_b32 s3, v252, 10
	s_waitcnt lgkmcnt(0)
	s_nop 3
	global_load_dword v0, v17, s[2:3] sc1
	s_waitcnt vmcnt(0)
	v_cmp_eq_u32_e32 vcc, v0, v1
	s_and_saveexec_b64 s[2:3], vcc
	s_cbranch_execz .LBB0_2010
	s_mov_b32 s16, 1
	s_mov_b64 s[6:7], 0
	s_branch .LBB0_2001

; __device__ __forceinline__ unsigned xb_ld(unsigned* p)              { return __hip_atomic_load(p, __ATOMIC_RELAXED, __HIP_MEMORY_SCOPE_AGENT); }
; #define XB_SPIN(cond, bar) do { unsigned _sp = 0; while (cond) { __builtin_amdgcn_s_sleep(0); \
;     if ((++_sp & 255u) == 0u) { if (xb_ld(&(bar)[XB_TMO])) break; if (_sp > XB_SPIN_CAP) { atomicAdd(&(bar)[XB_TMO], 1u); break; } } } } while (0)
; __device__ __forceinline__ void xcd_barrier(const XcdBarrier& b) {
;     ...
;             XB_SPIN(xb_ld(&bar[XB_XGEN(b.x)]) == gen, bar);
.LBB0_2005:
	v_readlane_b32 s10, v252, 9
	v_readlane_b32 s11, v252, 10
	s_add_i32 s16, s16, 1
	s_mov_b64 s[12:13], -1
	s_nop 2
	global_load_dword v0, v17, s[10:11] sc1
	s_waitcnt vmcnt(0)
	v_cmp_ne_u32_e32 vcc, v0, v1
	s_orn2_b64 s[10:11], vcc, exec
	s_branch .LBB0_2000
